# GEMM K-loop: the second s_waitcnt lgkmcnt(0) right after each phase barrier removed (nothing is issued between it and the identical wait before the barrier); loop head pinned at the same byte phase
# baseline (speedup 1.0000x reference)
; #define PG8_STAGE(bufoff, gbase, voff) do { _Pragma("unroll") for (int _i = 0; _i < 2; ++_i) \
;         __builtin_amdgcn_global_load_lds((const unsigned*)((const char*)(gbase) + (voff)[_i]), (LAS unsigned*)(lds + (bufoff) + ldsw + _i * 8192), 16, 0, 0); } while (0)
; #define PG8_LDA(dst, b, h) do { _Pragma("unroll") for (int m = 0; m < 4; ++m) _Pragma("unroll") for (int k = 0; k < 2; ++k) dst[m][k] = *(const LAS bf16x8*)(lds + PG8_SA(b, h) + aoff + m * 2048 + k * 1024); } while (0)
; #define PG8_LDB(dst, b, h) do { _Pragma("unroll") for (int n = 0; n < 2; ++n) _Pragma("unroll") for (int k = 0; k < 2; ++k) dst[n][k] = *(const LAS bf16x8*)(lds + PG8_SB(b, h) + boff + n * 2048 + k * 1024); } while (0)
; #define PG8_MMA(ai, bj, At, Bt) do { __builtin_amdgcn_s_setprio(1); _Pragma("unroll") for (int m = 0; m < 4; ++m) _Pragma("unroll") for (int n = 0; n < 2; ++n) _Pragma("unroll") for (int k = 0; k < 2; ++k) \
;         acc[ai][bj][m][n] = __builtin_amdgcn_mfma_f32_16x16x32_bf16(Bt[n][k], At[m][k], acc[ai][bj][m][n], 0, 0, 0); __builtin_amdgcn_s_setprio(0); } while (0)
; #define PG8_WAIT_V(n) asm volatile("s_waitcnt vmcnt(" #n ")" ::: "memory")
; #define PG8_BAR __builtin_amdgcn_s_barrier()
; __device__ __forceinline__ void gemm_phase(LAS unsigned char* lds, const GemmP g, const EpiP e) {
;     ...
;     for (;;) {
;         const bool has_next = unit_next(g, ui + 1, nxt);
;         const char* nA = has_next ? UNIT_A(nxt) : cA; const char* nB = has_next ? UNIT_B(nxt) : cB;
;         const int nt = cur.nt;
;         for (int t = 0; t < nt; t += 2) {
;             const bool last = (t == nt - 2);
;             const char* a1 = cA + (size_t)(t + 1) * kstepA;
;             const char* a2 = last ? nA : cA + (size_t)(t + 2) * kstepA; const char* b2 = last ? nB : cB + (size_t)(t + 2) * kstepB;
;             const char* a3 = a2 + kstepA; const char* b3 = b2 + kstepB;
;             PG8_LDB(B0, 0, 0); PG8_LDB(B1, 0, 1); PG8_SCHED; PG8_LDA(At, 0, 0); PG8_STAGE(PG8_SA(1, 1), a1 + hstepA, voffA);
;             PG8_WAIT_V(8); PG8_WAIT_L(0); PG8_BAR; PG8_MMA(0, 0, At, B0); PG8_MMA(0, 1, At, B1); PG8_BAR; PG8_SCHED;
;             PG8_LDA(At, 0, 1); PG8_STAGE(PG8_SB(0, 0), b2, voffB); PG8_STAGE(PG8_SB(0, 1), b2 + hstepB, voffB); PG8_STAGE(PG8_SA(0, 0), a2, voffA);
;             PG8_WAIT_V(8); PG8_WAIT_L(0); PG8_BAR; PG8_MMA(1, 0, At, B0); PG8_MMA(1, 1, At, B1); PG8_BAR; PG8_SCHED;
.LBB0_392:
	s_cmp_lt_i32 s69, 1
	s_cbranch_scc1 .LBB0_395
	s_add_u32 s24, s78, s90
	s_addc_u32 s25, s79, s7
	s_add_i32 s26, s69, -2
	s_add_u32 s27, s40, 0x100
	s_addc_u32 s28, s41, 0
	s_mov_b64 s[18:19], 0
	s_cmp_eq_u32 s99, 0
	s_cbranch_scc1 .LBB0_394
	s_mov_b32 s99, 0
	s_add_u32 s30, s18, 1
	s_addc_u32 s31, s19, 0
	s_add_u32 s16, s18, 2
	s_addc_u32 s17, s19, 0
	s_lshl_b64 s[20:21], s[16:17], s77
	s_add_u32 s19, s78, s20
	s_addc_u32 s20, s79, s21
	s_cmp_eq_u32 s26, s18
	s_cselect_b32 s21, s51, s20
	s_cselect_b32 s20, s50, s19
	s_cselect_b32 s22, s80, s27
	s_cselect_b32 s23, s81, s28
	s_add_u32 s18, s20, s38
	s_addc_u32 s19, s21, s39
	s_add_i32 s29, 0, 0x10000
	v_add_u32_e32 v96, s29, v179
	s_add_i32 s34, 0, 0x14000
	ds_read_b128 v[132:135], v96
	ds_read_b128 v[136:139], v96 offset:1024
	ds_read_b128 v[160:163], v96 offset:2048
	ds_read_b128 v[164:167], v96 offset:3072
	v_add_u32_e32 v96, s34, v179
	ds_read_b128 v[168:171], v96
	ds_read_b128 v[172:175], v96 offset:1024
	ds_read_b128 v[216:219], v96 offset:2048
	ds_read_b128 v[220:223], v96 offset:3072
	s_lshl_b64 s[30:31], s[30:31], s77
	s_add_u32 s30, s24, s30
	s_addc_u32 s31, s25, s31
	v_lshl_add_u64 v[98:99], s[30:31], 0, v[140:141]
	s_add_i32 m0, s92, 0xc000
	ds_read_b128 v[224:227], v188
	ds_read_b128 v[228:231], v188 offset:1024
	ds_read_b128 v[232:235], v188 offset:2048
	ds_read_b128 v[236:239], v188 offset:3072
	ds_read_b128 v[240:243], v188 offset:4096
	ds_read_b128 v[244:247], v188 offset:5120
	ds_read_b128 v[248:251], v188 offset:6144
	ds_read_b128 v[204:207], v188 offset:7168
	global_load_lds_dwordx4 v[98:99], off
	v_lshl_add_u64 v[98:99], s[30:31], 0, v[142:143]
	s_add_i32 m0, s92, 0xe000
	s_nop 0
	global_load_lds_dwordx4 v[98:99], off
	s_waitcnt vmcnt(24)
	s_waitcnt lgkmcnt(0)
	s_barrier
	s_setprio 1
	v_mfma_f32_16x16x32_bf16 v[128:131], v[132:135], v[224:227], v[128:131]
	v_mfma_f32_16x16x32_bf16 v[124:127], v[160:163], v[224:227], v[124:127]
	v_mfma_f32_16x16x32_bf16 v[120:123], v[132:135], v[232:235], v[120:123]
	v_mfma_f32_16x16x32_bf16 v[116:119], v[160:163], v[232:235], v[116:119]
	v_mfma_f32_16x16x32_bf16 v[112:115], v[132:135], v[240:243], v[112:115]
	v_mfma_f32_16x16x32_bf16 v[108:111], v[160:163], v[240:243], v[108:111]
	v_mfma_f32_16x16x32_bf16 v[104:107], v[132:135], v[248:251], v[104:107]
	v_mfma_f32_16x16x32_bf16 v[98:101], v[160:163], v[248:251], v[100:103]
	v_mfma_f32_16x16x32_bf16 v[128:131], v[136:139], v[228:231], v[128:131]
	v_mfma_f32_16x16x32_bf16 v[124:127], v[164:167], v[228:231], v[124:127]
	v_mfma_f32_16x16x32_bf16 v[120:123], v[136:139], v[236:239], v[120:123]
	v_mfma_f32_16x16x32_bf16 v[116:119], v[164:167], v[236:239], v[116:119]
	v_mfma_f32_16x16x32_bf16 v[112:115], v[136:139], v[244:247], v[112:115]
	v_mfma_f32_16x16x32_bf16 v[108:111], v[164:167], v[244:247], v[108:111]
	v_mfma_f32_16x16x32_bf16 v[104:107], v[136:139], v[204:207], v[104:107]
	v_mfma_f32_16x16x32_bf16 v[98:101], v[164:167], v[204:207], v[98:101]
	s_setprio 0
	s_setprio 1
	v_mfma_f32_16x16x32_bf16 v[92:95], v[168:171], v[224:227], v[92:95]
	v_mfma_f32_16x16x32_bf16 v[88:91], v[216:219], v[224:227], v[88:91]
	v_mfma_f32_16x16x32_bf16 v[84:87], v[168:171], v[232:235], v[84:87]
	v_mfma_f32_16x16x32_bf16 v[80:83], v[216:219], v[232:235], v[80:83]
	v_mfma_f32_16x16x32_bf16 v[76:79], v[168:171], v[240:243], v[76:79]
	v_mfma_f32_16x16x32_bf16 v[72:75], v[216:219], v[240:243], v[72:75]
	v_mfma_f32_16x16x32_bf16 v[68:71], v[168:171], v[248:251], v[68:71]
	v_mfma_f32_16x16x32_bf16 v[64:67], v[216:219], v[248:251], v[64:67]
	v_mfma_f32_16x16x32_bf16 v[92:95], v[172:175], v[228:231], v[92:95]
	v_mfma_f32_16x16x32_bf16 v[88:91], v[220:223], v[228:231], v[88:91]
	v_mfma_f32_16x16x32_bf16 v[84:87], v[172:175], v[236:239], v[84:87]
	v_mfma_f32_16x16x32_bf16 v[80:83], v[220:223], v[236:239], v[80:83]
	v_mfma_f32_16x16x32_bf16 v[76:79], v[172:175], v[244:247], v[76:79]
	v_mfma_f32_16x16x32_bf16 v[72:75], v[220:223], v[244:247], v[72:75]
	v_mfma_f32_16x16x32_bf16 v[68:71], v[172:175], v[204:207], v[68:71]
	v_mfma_f32_16x16x32_bf16 v[64:67], v[220:223], v[204:207], v[64:67]
	s_setprio 0
	s_barrier
	s_add_i32 s29, s29, s91
	v_lshl_add_u64 v[176:177], s[22:23], 0, v[146:147]
	s_mov_b32 m0, s29
	ds_read_b128 v[204:207], v188 offset:16384
	ds_read_b128 v[224:227], v188 offset:17408
	ds_read_b128 v[228:231], v188 offset:18432
	ds_read_b128 v[232:235], v188 offset:19456
	ds_read_b128 v[236:239], v188 offset:20480
	ds_read_b128 v[240:243], v188 offset:21504
	ds_read_b128 v[244:247], v188 offset:22528
	ds_read_b128 v[248:251], v188 offset:23552
	global_load_lds_dwordx4 v[176:177], off
	s_add_i32 m0, s29, 0x2000
	v_lshl_add_u64 v[210:211], s[22:23], 0, v[144:145]
	s_add_u32 s22, s22, s48
	s_addc_u32 s23, s23, s49
	s_add_i32 s29, s34, s91
	global_load_lds_dwordx4 v[210:211], off
	v_lshl_add_u64 v[212:213], s[22:23], 0, v[146:147]
	s_mov_b32 m0, s29
	v_lshl_add_u64 v[190:191], s[22:23], 0, v[144:145]
	global_load_lds_dwordx4 v[212:213], off
	s_add_i32 m0, s29, 0x2000
	v_lshl_add_u64 v[102:103], s[20:21], 0, v[140:141]
	global_load_lds_dwordx4 v[190:191], off
	s_mov_b32 m0, s92
	s_nop 0
	global_load_lds_dwordx4 v[102:103], off
	v_lshl_add_u64 v[102:103], s[20:21], 0, v[142:143]
	s_mov_b32 m0, s93
	s_nop 0
	global_load_lds_dwordx4 v[102:103], off
	s_waitcnt vmcnt(24)
	s_waitcnt lgkmcnt(0)
	s_barrier
; #define PG8_STAGE(bufoff, gbase, voff) do { _Pragma("unroll") for (int _i = 0; _i < 2; ++_i) \
;         __builtin_amdgcn_global_load_lds((const unsigned*)((const char*)(gbase) + (voff)[_i]), (LAS unsigned*)(lds + (bufoff) + ldsw + _i * 8192), 16, 0, 0); } while (0)
; #define PG8_LDA(dst, b, h) do { _Pragma("unroll") for (int m = 0; m < 4; ++m) _Pragma("unroll") for (int k = 0; k < 2; ++k) dst[m][k] = *(const LAS bf16x8*)(lds + PG8_SA(b, h) + aoff + m * 2048 + k * 1024); } while (0)
; #define PG8_LDB(dst, b, h) do { _Pragma("unroll") for (int n = 0; n < 2; ++n) _Pragma("unroll") for (int k = 0; k < 2; ++k) dst[n][k] = *(const LAS bf16x8*)(lds + PG8_SB(b, h) + boff + n * 2048 + k * 1024); } while (0)
; #define PG8_MMA(ai, bj, At, Bt) do { __builtin_amdgcn_s_setprio(1); _Pragma("unroll") for (int m = 0; m < 4; ++m) _Pragma("unroll") for (int n = 0; n < 2; ++n) _Pragma("unroll") for (int k = 0; k < 2; ++k) \
;         acc[ai][bj][m][n] = __builtin_amdgcn_mfma_f32_16x16x32_bf16(Bt[n][k], At[m][k], acc[ai][bj][m][n], 0, 0, 0); __builtin_amdgcn_s_setprio(0); } while (0)
; #define PG8_WAIT_V(n) asm volatile("s_waitcnt vmcnt(" #n ")" ::: "memory")
; #define PG8_WAIT_L(n) asm volatile("s_waitcnt lgkmcnt(" #n ")" ::: "memory")
; #define PG8_BAR __builtin_amdgcn_s_barrier()
; #define PG8_SCHED __builtin_amdgcn_sched_barrier(0)
; __device__ __forceinline__ void gemm_phase(LAS unsigned char* lds, const GemmP g, const EpiP e) {
;     ...
;             PG8_WAIT_V(8); PG8_WAIT_L(0); PG8_BAR; PG8_MMA(1, 0, At, B0); PG8_MMA(1, 1, At, B1); PG8_BAR; PG8_SCHED;
;             PG8_LDB(B0, 1, 0); PG8_LDB(B1, 1, 1); PG8_SCHED; PG8_LDA(At, 1, 0); PG8_STAGE(PG8_SA(0, 1), a2 + hstepA, voffA);
;             PG8_WAIT_V(8); PG8_WAIT_L(0); PG8_BAR; PG8_MMA(0, 0, At, B0); PG8_MMA(0, 1, At, B1); PG8_BAR; PG8_SCHED;
	s_setprio 1
	v_mfma_f32_16x16x32_bf16 v[60:63], v[132:135], v[204:207], v[60:63]
	v_mfma_f32_16x16x32_bf16 v[56:59], v[160:163], v[204:207], v[56:59]
	v_mfma_f32_16x16x32_bf16 v[52:55], v[132:135], v[228:231], v[52:55]
	v_mfma_f32_16x16x32_bf16 v[48:51], v[160:163], v[228:231], v[48:51]
	v_mfma_f32_16x16x32_bf16 v[44:47], v[132:135], v[236:239], v[44:47]
	v_mfma_f32_16x16x32_bf16 v[40:43], v[160:163], v[236:239], v[40:43]
	v_mfma_f32_16x16x32_bf16 v[36:39], v[132:135], v[244:247], v[36:39]
	v_mfma_f32_16x16x32_bf16 v[32:35], v[160:163], v[244:247], v[32:35]
	v_mfma_f32_16x16x32_bf16 v[60:63], v[136:139], v[224:227], v[60:63]
	v_mfma_f32_16x16x32_bf16 v[56:59], v[164:167], v[224:227], v[56:59]
	v_mfma_f32_16x16x32_bf16 v[52:55], v[136:139], v[232:235], v[52:55]
	v_mfma_f32_16x16x32_bf16 v[48:51], v[164:167], v[232:235], v[48:51]
	v_mfma_f32_16x16x32_bf16 v[44:47], v[136:139], v[240:243], v[44:47]
	v_mfma_f32_16x16x32_bf16 v[40:43], v[164:167], v[240:243], v[40:43]
	v_mfma_f32_16x16x32_bf16 v[36:39], v[136:139], v[248:251], v[36:39]
	v_mfma_f32_16x16x32_bf16 v[32:35], v[164:167], v[248:251], v[32:35]
	s_setprio 0
	s_setprio 1
	v_mfma_f32_16x16x32_bf16 v[28:31], v[168:171], v[204:207], v[28:31]
	v_mfma_f32_16x16x32_bf16 v[24:27], v[216:219], v[204:207], v[24:27]
	v_mfma_f32_16x16x32_bf16 v[20:23], v[168:171], v[228:231], v[20:23]
	v_mfma_f32_16x16x32_bf16 v[16:19], v[216:219], v[228:231], v[16:19]
	v_mfma_f32_16x16x32_bf16 v[12:15], v[168:171], v[236:239], v[12:15]
	v_mfma_f32_16x16x32_bf16 v[8:11], v[216:219], v[236:239], v[8:11]
	v_mfma_f32_16x16x32_bf16 v[4:7], v[168:171], v[244:247], v[4:7]
	v_mfma_f32_16x16x32_bf16 v[0:3], v[216:219], v[244:247], v[0:3]
	v_mfma_f32_16x16x32_bf16 v[28:31], v[172:175], v[224:227], v[28:31]
	v_mfma_f32_16x16x32_bf16 v[24:27], v[220:223], v[224:227], v[24:27]
	v_mfma_f32_16x16x32_bf16 v[20:23], v[172:175], v[232:235], v[20:23]
	v_mfma_f32_16x16x32_bf16 v[16:19], v[220:223], v[232:235], v[16:19]
	v_mfma_f32_16x16x32_bf16 v[12:15], v[172:175], v[240:243], v[12:15]
	v_mfma_f32_16x16x32_bf16 v[8:11], v[220:223], v[240:243], v[8:11]
	v_mfma_f32_16x16x32_bf16 v[4:7], v[172:175], v[248:251], v[4:7]
	v_mfma_f32_16x16x32_bf16 v[0:3], v[220:223], v[248:251], v[0:3]
	s_setprio 0
	s_barrier
	s_add_i32 s22, 0, 0x18000
	v_add_u32_e32 v96, s22, v179
	s_add_i32 s23, 0, 0x1c000
	ds_read_b128 v[132:135], v96
	ds_read_b128 v[136:139], v96 offset:1024
	ds_read_b128 v[160:163], v96 offset:2048
	ds_read_b128 v[164:167], v96 offset:3072
	v_add_u32_e32 v96, s23, v179
	ds_read_b128 v[168:171], v96
	ds_read_b128 v[172:175], v96 offset:1024
	ds_read_b128 v[204:207], v96 offset:2048
	ds_read_b128 v[216:219], v96 offset:3072
	s_add_u32 s20, s20, s90
	s_addc_u32 s21, s21, s7
	s_mov_b32 m0, s73
	v_lshl_add_u64 v[102:103], s[20:21], 0, v[140:141]
	ds_read_b128 v[220:223], v188 offset:32768
	ds_read_b128 v[224:227], v188 offset:33792
	ds_read_b128 v[228:231], v188 offset:34816
	ds_read_b128 v[232:235], v188 offset:35840
	ds_read_b128 v[236:239], v188 offset:36864
	ds_read_b128 v[240:243], v188 offset:37888
	ds_read_b128 v[244:247], v188 offset:38912
	ds_read_b128 v[248:251], v188 offset:39936
	global_load_lds_dwordx4 v[102:103], off
	v_lshl_add_u64 v[102:103], s[20:21], 0, v[142:143]
	s_mov_b32 m0, s4
	s_nop 0
	global_load_lds_dwordx4 v[102:103], off
	s_waitcnt vmcnt(8)
	s_waitcnt lgkmcnt(0)
	s_barrier
	s_setprio 1
	v_mfma_f32_16x16x32_bf16 v[128:131], v[132:135], v[220:223], v[128:131]
	v_mfma_f32_16x16x32_bf16 v[124:127], v[160:163], v[220:223], v[124:127]
	v_mfma_f32_16x16x32_bf16 v[120:123], v[132:135], v[228:231], v[120:123]
	v_mfma_f32_16x16x32_bf16 v[116:119], v[160:163], v[228:231], v[116:119]
	v_mfma_f32_16x16x32_bf16 v[112:115], v[132:135], v[236:239], v[112:115]
	v_mfma_f32_16x16x32_bf16 v[108:111], v[160:163], v[236:239], v[108:111]
	v_mfma_f32_16x16x32_bf16 v[102:105], v[132:135], v[244:247], v[104:107]
	v_mfma_f32_16x16x32_bf16 v[98:101], v[160:163], v[244:247], v[98:101]
	v_mfma_f32_16x16x32_bf16 v[128:131], v[136:139], v[224:227], v[128:131]
	v_mfma_f32_16x16x32_bf16 v[124:127], v[164:167], v[224:227], v[124:127]
	v_mfma_f32_16x16x32_bf16 v[120:123], v[136:139], v[232:235], v[120:123]
	v_mfma_f32_16x16x32_bf16 v[116:119], v[164:167], v[232:235], v[116:119]
	v_mfma_f32_16x16x32_bf16 v[112:115], v[136:139], v[240:243], v[112:115]
	v_mfma_f32_16x16x32_bf16 v[108:111], v[164:167], v[240:243], v[108:111]
	v_mfma_f32_16x16x32_bf16 v[104:107], v[136:139], v[248:251], v[102:105]
	v_mfma_f32_16x16x32_bf16 v[100:103], v[164:167], v[248:251], v[98:101]
	s_setprio 0
	s_setprio 1
	v_mfma_f32_16x16x32_bf16 v[92:95], v[168:171], v[220:223], v[92:95]
	v_mfma_f32_16x16x32_bf16 v[88:91], v[204:207], v[220:223], v[88:91]
	v_mfma_f32_16x16x32_bf16 v[84:87], v[168:171], v[228:231], v[84:87]
	v_mfma_f32_16x16x32_bf16 v[80:83], v[204:207], v[228:231], v[80:83]
	v_mfma_f32_16x16x32_bf16 v[76:79], v[168:171], v[236:239], v[76:79]
	v_mfma_f32_16x16x32_bf16 v[72:75], v[204:207], v[236:239], v[72:75]
	v_mfma_f32_16x16x32_bf16 v[68:71], v[168:171], v[244:247], v[68:71]
	v_mfma_f32_16x16x32_bf16 v[64:67], v[204:207], v[244:247], v[64:67]
	v_mfma_f32_16x16x32_bf16 v[92:95], v[172:175], v[224:227], v[92:95]
	v_mfma_f32_16x16x32_bf16 v[88:91], v[216:219], v[224:227], v[88:91]
	v_mfma_f32_16x16x32_bf16 v[84:87], v[172:175], v[232:235], v[84:87]
	v_mfma_f32_16x16x32_bf16 v[80:83], v[216:219], v[232:235], v[80:83]
	v_mfma_f32_16x16x32_bf16 v[76:79], v[172:175], v[240:243], v[76:79]
	v_mfma_f32_16x16x32_bf16 v[72:75], v[216:219], v[240:243], v[72:75]
	v_mfma_f32_16x16x32_bf16 v[68:71], v[172:175], v[248:251], v[68:71]
	v_mfma_f32_16x16x32_bf16 v[64:67], v[216:219], v[248:251], v[64:67]
	s_setprio 0
	s_barrier
; #define PG8_STAGE(bufoff, gbase, voff) do { _Pragma("unroll") for (int _i = 0; _i < 2; ++_i) \
;         __builtin_amdgcn_global_load_lds((const unsigned*)((const char*)(gbase) + (voff)[_i]), (LAS unsigned*)(lds + (bufoff) + ldsw + _i * 8192), 16, 0, 0); } while (0)
; #define PG8_LDA(dst, b, h) do { _Pragma("unroll") for (int m = 0; m < 4; ++m) _Pragma("unroll") for (int k = 0; k < 2; ++k) dst[m][k] = *(const LAS bf16x8*)(lds + PG8_SA(b, h) + aoff + m * 2048 + k * 1024); } while (0)
; #define PG8_LDB(dst, b, h) do { _Pragma("unroll") for (int n = 0; n < 2; ++n) _Pragma("unroll") for (int k = 0; k < 2; ++k) dst[n][k] = *(const LAS bf16x8*)(lds + PG8_SB(b, h) + boff + n * 2048 + k * 1024); } while (0)
; #define PG8_MMA(ai, bj, At, Bt) do { __builtin_amdgcn_s_setprio(1); _Pragma("unroll") for (int m = 0; m < 4; ++m) _Pragma("unroll") for (int n = 0; n < 2; ++n) _Pragma("unroll") for (int k = 0; k < 2; ++k) \
;         acc[ai][bj][m][n] = __builtin_amdgcn_mfma_f32_16x16x32_bf16(Bt[n][k], At[m][k], acc[ai][bj][m][n], 0, 0, 0); __builtin_amdgcn_s_setprio(0); } while (0)
; #define PG8_WAIT_V(n) asm volatile("s_waitcnt vmcnt(" #n ")" ::: "memory")
; #define PG8_WAIT_L(n) asm volatile("s_waitcnt lgkmcnt(" #n ")" ::: "memory")
; #define PG8_BAR __builtin_amdgcn_s_barrier()
; #define PG8_SCHED __builtin_amdgcn_sched_barrier(0)
; __device__ __forceinline__ void gemm_phase(LAS unsigned char* lds, const GemmP g, const EpiP e) {
;     ...
;         for (int t = 0; t < nt; t += 2) {
;             const bool last = (t == nt - 2);
;             const char* a1 = cA + (size_t)(t + 1) * kstepA;
;             const char* a2 = last ? nA : cA + (size_t)(t + 2) * kstepA; const char* b2 = last ? nB : cB + (size_t)(t + 2) * kstepB;
;             const char* a3 = a2 + kstepA; const char* b3 = b2 + kstepB;
;             PG8_LDB(B0, 0, 0); PG8_LDB(B1, 0, 1); PG8_SCHED; PG8_LDA(At, 0, 0); PG8_STAGE(PG8_SA(1, 1), a1 + hstepA, voffA);
;             PG8_WAIT_V(8); PG8_WAIT_L(0); PG8_BAR; PG8_MMA(0, 0, At, B0); PG8_MMA(0, 1, At, B1); PG8_BAR; PG8_SCHED;
;     ...
;             PG8_LDA(At, 1, 1); PG8_STAGE(PG8_SB(1, 0), b3, voffB); PG8_STAGE(PG8_SB(1, 1), b3 + hstepB, voffB); PG8_STAGE(PG8_SA(1, 0), a3, voffA);
;             PG8_WAIT_V(8); PG8_WAIT_L(0); PG8_BAR; PG8_MMA(1, 0, At, B0); PG8_MMA(1, 1, At, B1); PG8_BAR; PG8_SCHED;
	s_add_i32 s20, s22, s91
	v_lshl_add_u64 v[98:99], v[176:177], 0, s[96:97]
	s_mov_b32 m0, s20
	ds_read_b128 v[220:223], v188 offset:49152
	ds_read_b128 v[224:227], v188 offset:50176
	ds_read_b128 v[228:231], v188 offset:51200
	ds_read_b128 v[232:235], v188 offset:52224
	ds_read_b128 v[236:239], v188 offset:53248
	ds_read_b128 v[240:243], v188 offset:54272
	ds_read_b128 v[244:247], v188 offset:55296
	ds_read_b128 v[248:251], v188 offset:56320
	global_load_lds_dwordx4 v[98:99], off
	v_lshl_add_u64 v[98:99], v[210:211], 0, s[96:97]
	s_add_i32 m0, s20, 0x2000
	s_add_i32 s20, s23, s91
	global_load_lds_dwordx4 v[98:99], off
	v_lshl_add_u64 v[98:99], v[212:213], 0, s[96:97]
	s_mov_b32 m0, s20
	s_nop 0
	global_load_lds_dwordx4 v[98:99], off
	v_lshl_add_u64 v[98:99], v[190:191], 0, s[96:97]
	s_add_i32 m0, s20, 0x2000
	s_nop 0
	global_load_lds_dwordx4 v[98:99], off
	v_lshl_add_u64 v[98:99], s[18:19], 0, v[140:141]
	s_mov_b32 m0, s5
	s_nop 0
	global_load_lds_dwordx4 v[98:99], off
	v_lshl_add_u64 v[98:99], s[18:19], 0, v[142:143]
	s_mov_b32 m0, s44
	s_nop 0
	global_load_lds_dwordx4 v[98:99], off
	s_waitcnt vmcnt(8)
	s_waitcnt lgkmcnt(0)
	s_barrier
	s_setprio 1
	v_mfma_f32_16x16x32_bf16 v[60:63], v[132:135], v[220:223], v[60:63]
	v_mfma_f32_16x16x32_bf16 v[56:59], v[160:163], v[220:223], v[56:59]
	v_mfma_f32_16x16x32_bf16 v[52:55], v[132:135], v[228:231], v[52:55]
	v_mfma_f32_16x16x32_bf16 v[48:51], v[160:163], v[228:231], v[48:51]
	v_mfma_f32_16x16x32_bf16 v[44:47], v[132:135], v[236:239], v[44:47]
	v_mfma_f32_16x16x32_bf16 v[40:43], v[160:163], v[236:239], v[40:43]
	v_mfma_f32_16x16x32_bf16 v[36:39], v[132:135], v[244:247], v[36:39]
	v_mfma_f32_16x16x32_bf16 v[32:35], v[160:163], v[244:247], v[32:35]
	v_mfma_f32_16x16x32_bf16 v[60:63], v[136:139], v[224:227], v[60:63]
	v_mfma_f32_16x16x32_bf16 v[56:59], v[164:167], v[224:227], v[56:59]
	v_mfma_f32_16x16x32_bf16 v[52:55], v[136:139], v[232:235], v[52:55]
	v_mfma_f32_16x16x32_bf16 v[48:51], v[164:167], v[232:235], v[48:51]
	v_mfma_f32_16x16x32_bf16 v[44:47], v[136:139], v[240:243], v[44:47]
	v_mfma_f32_16x16x32_bf16 v[40:43], v[164:167], v[240:243], v[40:43]
	v_mfma_f32_16x16x32_bf16 v[36:39], v[136:139], v[248:251], v[36:39]
	v_mfma_f32_16x16x32_bf16 v[32:35], v[164:167], v[248:251], v[32:35]
	s_setprio 0
	s_setprio 1
	v_mfma_f32_16x16x32_bf16 v[28:31], v[168:171], v[220:223], v[28:31]
	v_mfma_f32_16x16x32_bf16 v[24:27], v[204:207], v[220:223], v[24:27]
	v_mfma_f32_16x16x32_bf16 v[20:23], v[168:171], v[228:231], v[20:23]
	v_mfma_f32_16x16x32_bf16 v[16:19], v[204:207], v[228:231], v[16:19]
	v_mfma_f32_16x16x32_bf16 v[12:15], v[168:171], v[236:239], v[12:15]
	v_mfma_f32_16x16x32_bf16 v[8:11], v[204:207], v[236:239], v[8:11]
	v_mfma_f32_16x16x32_bf16 v[4:7], v[168:171], v[244:247], v[4:7]
	v_mfma_f32_16x16x32_bf16 v[0:3], v[204:207], v[244:247], v[0:3]
	v_mfma_f32_16x16x32_bf16 v[28:31], v[172:175], v[224:227], v[28:31]
	v_mfma_f32_16x16x32_bf16 v[24:27], v[216:219], v[224:227], v[24:27]
	v_mfma_f32_16x16x32_bf16 v[20:23], v[172:175], v[232:235], v[20:23]
	v_mfma_f32_16x16x32_bf16 v[16:19], v[216:219], v[232:235], v[16:19]
	v_mfma_f32_16x16x32_bf16 v[12:15], v[172:175], v[240:243], v[12:15]
	v_mfma_f32_16x16x32_bf16 v[8:11], v[216:219], v[240:243], v[8:11]
	v_mfma_f32_16x16x32_bf16 v[4:7], v[172:175], v[248:251], v[4:7]
	v_mfma_f32_16x16x32_bf16 v[0:3], v[216:219], v[248:251], v[0:3]
	s_setprio 0
	s_barrier
	s_add_u32 s27, s27, 0x100
	s_addc_u32 s28, s28, 0
	s_cmp_ge_i32 s16, s69
	s_mov_b64 s[18:19], s[16:17]
	s_cbranch_scc0 .LBB0_394
	s_branch .LBB0_395
	.p2align 6
	s_nop 0
	s_nop 0
	s_nop 0
	s_nop 0
	s_nop 0
	s_nop 0
	s_nop 0
	s_nop 0
.LBB0_394:
	s_add_u32 s30, s18, 1
	s_addc_u32 s31, s19, 0
	s_add_u32 s16, s18, 2
	s_addc_u32 s17, s19, 0
	s_lshl_b64 s[20:21], s[16:17], s77
	s_add_u32 s19, s78, s20
	s_addc_u32 s20, s79, s21
	s_cmp_eq_u32 s26, s18
	s_cselect_b32 s21, s51, s20
	s_cselect_b32 s20, s50, s19
	s_cselect_b32 s22, s80, s27
	s_cselect_b32 s23, s81, s28
	s_add_u32 s18, s20, s38
	s_addc_u32 s19, s21, s39
	s_add_i32 s29, 0, 0x10000
	v_add_u32_e32 v96, s29, v179
	s_add_i32 s34, 0, 0x14000
	ds_read_b128 v[132:135], v96
	ds_read_b128 v[136:139], v96 offset:1024
	ds_read_b128 v[160:163], v96 offset:2048
	ds_read_b128 v[164:167], v96 offset:3072
	v_add_u32_e32 v96, s34, v179
	ds_read_b128 v[168:171], v96
	ds_read_b128 v[172:175], v96 offset:1024
	ds_read_b128 v[216:219], v96 offset:2048
	ds_read_b128 v[220:223], v96 offset:3072
	s_lshl_b64 s[30:31], s[30:31], s77
	s_add_u32 s30, s24, s30
	s_addc_u32 s31, s25, s31
	v_lshl_add_u64 v[98:99], s[30:31], 0, v[140:141]
	s_add_i32 m0, s92, 0xc000
	ds_read_b128 v[224:227], v188
	ds_read_b128 v[228:231], v188 offset:1024
	ds_read_b128 v[232:235], v188 offset:2048
	ds_read_b128 v[236:239], v188 offset:3072
	ds_read_b128 v[240:243], v188 offset:4096
	ds_read_b128 v[244:247], v188 offset:5120
	ds_read_b128 v[248:251], v188 offset:6144
	ds_read_b128 v[204:207], v188 offset:7168
	global_load_lds_dwordx4 v[98:99], off
	v_lshl_add_u64 v[98:99], s[30:31], 0, v[142:143]
	s_add_i32 m0, s92, 0xe000
	s_nop 0
	global_load_lds_dwordx4 v[98:99], off
	s_waitcnt vmcnt(8)
	s_waitcnt lgkmcnt(0)
	s_barrier
; #define PG8_STAGE(bufoff, gbase, voff) do { _Pragma("unroll") for (int _i = 0; _i < 2; ++_i) \
;         __builtin_amdgcn_global_load_lds((const unsigned*)((const char*)(gbase) + (voff)[_i]), (LAS unsigned*)(lds + (bufoff) + ldsw + _i * 8192), 16, 0, 0); } while (0)
; #define PG8_LDA(dst, b, h) do { _Pragma("unroll") for (int m = 0; m < 4; ++m) _Pragma("unroll") for (int k = 0; k < 2; ++k) dst[m][k] = *(const LAS bf16x8*)(lds + PG8_SA(b, h) + aoff + m * 2048 + k * 1024); } while (0)
; #define PG8_LDB(dst, b, h) do { _Pragma("unroll") for (int n = 0; n < 2; ++n) _Pragma("unroll") for (int k = 0; k < 2; ++k) dst[n][k] = *(const LAS bf16x8*)(lds + PG8_SB(b, h) + boff + n * 2048 + k * 1024); } while (0)
; #define PG8_MMA(ai, bj, At, Bt) do { __builtin_amdgcn_s_setprio(1); _Pragma("unroll") for (int m = 0; m < 4; ++m) _Pragma("unroll") for (int n = 0; n < 2; ++n) _Pragma("unroll") for (int k = 0; k < 2; ++k) \
;         acc[ai][bj][m][n] = __builtin_amdgcn_mfma_f32_16x16x32_bf16(Bt[n][k], At[m][k], acc[ai][bj][m][n], 0, 0, 0); __builtin_amdgcn_s_setprio(0); } while (0)
; #define PG8_WAIT_V(n) asm volatile("s_waitcnt vmcnt(" #n ")" ::: "memory")
; #define PG8_WAIT_L(n) asm volatile("s_waitcnt lgkmcnt(" #n ")" ::: "memory")
; #define PG8_BAR __builtin_amdgcn_s_barrier()
; #define PG8_SCHED __builtin_amdgcn_sched_barrier(0)
; __device__ __forceinline__ void gemm_phase(LAS unsigned char* lds, const GemmP g, const EpiP e) {
;     ...
;             PG8_WAIT_V(8); PG8_WAIT_L(0); PG8_BAR; PG8_MMA(0, 0, At, B0); PG8_MMA(0, 1, At, B1); PG8_BAR; PG8_SCHED;
;             PG8_LDA(At, 0, 1); PG8_STAGE(PG8_SB(0, 0), b2, voffB); PG8_STAGE(PG8_SB(0, 1), b2 + hstepB, voffB); PG8_STAGE(PG8_SA(0, 0), a2, voffA);
;             PG8_WAIT_V(8); PG8_WAIT_L(0); PG8_BAR; PG8_MMA(1, 0, At, B0); PG8_MMA(1, 1, At, B1); PG8_BAR; PG8_SCHED;
;             PG8_LDB(B0, 1, 0); PG8_LDB(B1, 1, 1); PG8_SCHED; PG8_LDA(At, 1, 0); PG8_STAGE(PG8_SA(0, 1), a2 + hstepA, voffA);
	s_setprio 1
	v_mfma_f32_16x16x32_bf16 v[128:131], v[132:135], v[224:227], v[128:131]
	v_mfma_f32_16x16x32_bf16 v[124:127], v[160:163], v[224:227], v[124:127]
	v_mfma_f32_16x16x32_bf16 v[120:123], v[132:135], v[232:235], v[120:123]
	v_mfma_f32_16x16x32_bf16 v[116:119], v[160:163], v[232:235], v[116:119]
	v_mfma_f32_16x16x32_bf16 v[112:115], v[132:135], v[240:243], v[112:115]
	v_mfma_f32_16x16x32_bf16 v[108:111], v[160:163], v[240:243], v[108:111]
	v_mfma_f32_16x16x32_bf16 v[104:107], v[132:135], v[248:251], v[104:107]
	v_mfma_f32_16x16x32_bf16 v[98:101], v[160:163], v[248:251], v[100:103]
	v_mfma_f32_16x16x32_bf16 v[128:131], v[136:139], v[228:231], v[128:131]
	v_mfma_f32_16x16x32_bf16 v[124:127], v[164:167], v[228:231], v[124:127]
	v_mfma_f32_16x16x32_bf16 v[120:123], v[136:139], v[236:239], v[120:123]
	v_mfma_f32_16x16x32_bf16 v[116:119], v[164:167], v[236:239], v[116:119]
	v_mfma_f32_16x16x32_bf16 v[112:115], v[136:139], v[244:247], v[112:115]
	v_mfma_f32_16x16x32_bf16 v[108:111], v[164:167], v[244:247], v[108:111]
	v_mfma_f32_16x16x32_bf16 v[104:107], v[136:139], v[204:207], v[104:107]
	v_mfma_f32_16x16x32_bf16 v[98:101], v[164:167], v[204:207], v[98:101]
	s_setprio 0
	s_setprio 1
	v_mfma_f32_16x16x32_bf16 v[92:95], v[168:171], v[224:227], v[92:95]
	v_mfma_f32_16x16x32_bf16 v[88:91], v[216:219], v[224:227], v[88:91]
	v_mfma_f32_16x16x32_bf16 v[84:87], v[168:171], v[232:235], v[84:87]
	v_mfma_f32_16x16x32_bf16 v[80:83], v[216:219], v[232:235], v[80:83]
	v_mfma_f32_16x16x32_bf16 v[76:79], v[168:171], v[240:243], v[76:79]
	v_mfma_f32_16x16x32_bf16 v[72:75], v[216:219], v[240:243], v[72:75]
	v_mfma_f32_16x16x32_bf16 v[68:71], v[168:171], v[248:251], v[68:71]
	v_mfma_f32_16x16x32_bf16 v[64:67], v[216:219], v[248:251], v[64:67]
	v_mfma_f32_16x16x32_bf16 v[92:95], v[172:175], v[228:231], v[92:95]
	v_mfma_f32_16x16x32_bf16 v[88:91], v[220:223], v[228:231], v[88:91]
	v_mfma_f32_16x16x32_bf16 v[84:87], v[172:175], v[236:239], v[84:87]
	v_mfma_f32_16x16x32_bf16 v[80:83], v[220:223], v[236:239], v[80:83]
	v_mfma_f32_16x16x32_bf16 v[76:79], v[172:175], v[244:247], v[76:79]
	v_mfma_f32_16x16x32_bf16 v[72:75], v[220:223], v[244:247], v[72:75]
	v_mfma_f32_16x16x32_bf16 v[68:71], v[172:175], v[204:207], v[68:71]
	v_mfma_f32_16x16x32_bf16 v[64:67], v[220:223], v[204:207], v[64:67]
	s_setprio 0
	s_barrier
	s_add_i32 s29, s29, s91
	v_lshl_add_u64 v[176:177], s[22:23], 0, v[146:147]
	s_mov_b32 m0, s29
	ds_read_b128 v[204:207], v188 offset:16384
	ds_read_b128 v[224:227], v188 offset:17408
	ds_read_b128 v[228:231], v188 offset:18432
	ds_read_b128 v[232:235], v188 offset:19456
	ds_read_b128 v[236:239], v188 offset:20480
	ds_read_b128 v[240:243], v188 offset:21504
	ds_read_b128 v[244:247], v188 offset:22528
	ds_read_b128 v[248:251], v188 offset:23552
	global_load_lds_dwordx4 v[176:177], off
	s_add_i32 m0, s29, 0x2000
	v_lshl_add_u64 v[210:211], s[22:23], 0, v[144:145]
	s_add_u32 s22, s22, s48
	s_addc_u32 s23, s23, s49
	s_add_i32 s29, s34, s91
	global_load_lds_dwordx4 v[210:211], off
	v_lshl_add_u64 v[212:213], s[22:23], 0, v[146:147]
	s_mov_b32 m0, s29
	v_lshl_add_u64 v[190:191], s[22:23], 0, v[144:145]
	global_load_lds_dwordx4 v[212:213], off
	s_add_i32 m0, s29, 0x2000
	v_lshl_add_u64 v[102:103], s[20:21], 0, v[140:141]
	global_load_lds_dwordx4 v[190:191], off
	s_mov_b32 m0, s92
	s_nop 0
	global_load_lds_dwordx4 v[102:103], off
	v_lshl_add_u64 v[102:103], s[20:21], 0, v[142:143]
	s_mov_b32 m0, s93
	s_nop 0
	global_load_lds_dwordx4 v[102:103], off
	s_waitcnt vmcnt(8)
	s_waitcnt lgkmcnt(0)
	s_barrier
	s_setprio 1
	v_mfma_f32_16x16x32_bf16 v[60:63], v[132:135], v[204:207], v[60:63]
	v_mfma_f32_16x16x32_bf16 v[56:59], v[160:163], v[204:207], v[56:59]
	v_mfma_f32_16x16x32_bf16 v[52:55], v[132:135], v[228:231], v[52:55]
	v_mfma_f32_16x16x32_bf16 v[48:51], v[160:163], v[228:231], v[48:51]
	v_mfma_f32_16x16x32_bf16 v[44:47], v[132:135], v[236:239], v[44:47]
	v_mfma_f32_16x16x32_bf16 v[40:43], v[160:163], v[236:239], v[40:43]
	v_mfma_f32_16x16x32_bf16 v[36:39], v[132:135], v[244:247], v[36:39]
	v_mfma_f32_16x16x32_bf16 v[32:35], v[160:163], v[244:247], v[32:35]
	v_mfma_f32_16x16x32_bf16 v[60:63], v[136:139], v[224:227], v[60:63]
	v_mfma_f32_16x16x32_bf16 v[56:59], v[164:167], v[224:227], v[56:59]
	v_mfma_f32_16x16x32_bf16 v[52:55], v[136:139], v[232:235], v[52:55]
	v_mfma_f32_16x16x32_bf16 v[48:51], v[164:167], v[232:235], v[48:51]
	v_mfma_f32_16x16x32_bf16 v[44:47], v[136:139], v[240:243], v[44:47]
	v_mfma_f32_16x16x32_bf16 v[40:43], v[164:167], v[240:243], v[40:43]
	v_mfma_f32_16x16x32_bf16 v[36:39], v[136:139], v[248:251], v[36:39]
	v_mfma_f32_16x16x32_bf16 v[32:35], v[164:167], v[248:251], v[32:35]
	s_setprio 0
	s_setprio 1
	v_mfma_f32_16x16x32_bf16 v[28:31], v[168:171], v[204:207], v[28:31]
	v_mfma_f32_16x16x32_bf16 v[24:27], v[216:219], v[204:207], v[24:27]
	v_mfma_f32_16x16x32_bf16 v[20:23], v[168:171], v[228:231], v[20:23]
	v_mfma_f32_16x16x32_bf16 v[16:19], v[216:219], v[228:231], v[16:19]
	v_mfma_f32_16x16x32_bf16 v[12:15], v[168:171], v[236:239], v[12:15]
	v_mfma_f32_16x16x32_bf16 v[8:11], v[216:219], v[236:239], v[8:11]
	v_mfma_f32_16x16x32_bf16 v[4:7], v[168:171], v[244:247], v[4:7]
	v_mfma_f32_16x16x32_bf16 v[0:3], v[216:219], v[244:247], v[0:3]
	v_mfma_f32_16x16x32_bf16 v[28:31], v[172:175], v[224:227], v[28:31]
	v_mfma_f32_16x16x32_bf16 v[24:27], v[220:223], v[224:227], v[24:27]
	v_mfma_f32_16x16x32_bf16 v[20:23], v[172:175], v[232:235], v[20:23]
	v_mfma_f32_16x16x32_bf16 v[16:19], v[220:223], v[232:235], v[16:19]
	v_mfma_f32_16x16x32_bf16 v[12:15], v[172:175], v[240:243], v[12:15]
	v_mfma_f32_16x16x32_bf16 v[8:11], v[220:223], v[240:243], v[8:11]
	v_mfma_f32_16x16x32_bf16 v[4:7], v[172:175], v[248:251], v[4:7]
	v_mfma_f32_16x16x32_bf16 v[0:3], v[220:223], v[248:251], v[0:3]
	s_setprio 0
	s_barrier
; #define PG8_STAGE(bufoff, gbase, voff) do { _Pragma("unroll") for (int _i = 0; _i < 2; ++_i) \
;         __builtin_amdgcn_global_load_lds((const unsigned*)((const char*)(gbase) + (voff)[_i]), (LAS unsigned*)(lds + (bufoff) + ldsw + _i * 8192), 16, 0, 0); } while (0)
; #define PG8_LDA(dst, b, h) do { _Pragma("unroll") for (int m = 0; m < 4; ++m) _Pragma("unroll") for (int k = 0; k < 2; ++k) dst[m][k] = *(const LAS bf16x8*)(lds + PG8_SA(b, h) + aoff + m * 2048 + k * 1024); } while (0)
; #define PG8_LDB(dst, b, h) do { _Pragma("unroll") for (int n = 0; n < 2; ++n) _Pragma("unroll") for (int k = 0; k < 2; ++k) dst[n][k] = *(const LAS bf16x8*)(lds + PG8_SB(b, h) + boff + n * 2048 + k * 1024); } while (0)
; #define PG8_MMA(ai, bj, At, Bt) do { __builtin_amdgcn_s_setprio(1); _Pragma("unroll") for (int m = 0; m < 4; ++m) _Pragma("unroll") for (int n = 0; n < 2; ++n) _Pragma("unroll") for (int k = 0; k < 2; ++k) \
;         acc[ai][bj][m][n] = __builtin_amdgcn_mfma_f32_16x16x32_bf16(Bt[n][k], At[m][k], acc[ai][bj][m][n], 0, 0, 0); __builtin_amdgcn_s_setprio(0); } while (0)
; #define PG8_WAIT_V(n) asm volatile("s_waitcnt vmcnt(" #n ")" ::: "memory")
; #define PG8_WAIT_L(n) asm volatile("s_waitcnt lgkmcnt(" #n ")" ::: "memory")
; #define PG8_BAR __builtin_amdgcn_s_barrier()
; #define PG8_SCHED __builtin_amdgcn_sched_barrier(0)
; __device__ __forceinline__ void gemm_phase(LAS unsigned char* lds, const GemmP g, const EpiP e) {
;     ...
;             PG8_LDB(B0, 1, 0); PG8_LDB(B1, 1, 1); PG8_SCHED; PG8_LDA(At, 1, 0); PG8_STAGE(PG8_SA(0, 1), a2 + hstepA, voffA);
;             PG8_WAIT_V(8); PG8_WAIT_L(0); PG8_BAR; PG8_MMA(0, 0, At, B0); PG8_MMA(0, 1, At, B1); PG8_BAR; PG8_SCHED;
;             PG8_LDA(At, 1, 1); PG8_STAGE(PG8_SB(1, 0), b3, voffB); PG8_STAGE(PG8_SB(1, 1), b3 + hstepB, voffB); PG8_STAGE(PG8_SA(1, 0), a3, voffA);
;             PG8_WAIT_V(8); PG8_WAIT_L(0); PG8_BAR; PG8_MMA(1, 0, At, B0); PG8_MMA(1, 1, At, B1); PG8_BAR; PG8_SCHED;
	s_add_i32 s22, 0, 0x18000
	v_add_u32_e32 v96, s22, v179
	s_add_i32 s23, 0, 0x1c000
	ds_read_b128 v[132:135], v96
	ds_read_b128 v[136:139], v96 offset:1024
	ds_read_b128 v[160:163], v96 offset:2048
	ds_read_b128 v[164:167], v96 offset:3072
	v_add_u32_e32 v96, s23, v179
	ds_read_b128 v[168:171], v96
	ds_read_b128 v[172:175], v96 offset:1024
	ds_read_b128 v[204:207], v96 offset:2048
	ds_read_b128 v[216:219], v96 offset:3072
	s_add_u32 s20, s20, s90
	s_addc_u32 s21, s21, s7
	s_mov_b32 m0, s73
	v_lshl_add_u64 v[102:103], s[20:21], 0, v[140:141]
	ds_read_b128 v[220:223], v188 offset:32768
	ds_read_b128 v[224:227], v188 offset:33792
	ds_read_b128 v[228:231], v188 offset:34816
	ds_read_b128 v[232:235], v188 offset:35840
	ds_read_b128 v[236:239], v188 offset:36864
	ds_read_b128 v[240:243], v188 offset:37888
	ds_read_b128 v[244:247], v188 offset:38912
	ds_read_b128 v[248:251], v188 offset:39936
	global_load_lds_dwordx4 v[102:103], off
	v_lshl_add_u64 v[102:103], s[20:21], 0, v[142:143]
	s_mov_b32 m0, s4
	s_nop 0
	global_load_lds_dwordx4 v[102:103], off
	s_waitcnt vmcnt(8)
	s_waitcnt lgkmcnt(0)
	s_barrier
	s_setprio 1
	v_mfma_f32_16x16x32_bf16 v[128:131], v[132:135], v[220:223], v[128:131]
	v_mfma_f32_16x16x32_bf16 v[124:127], v[160:163], v[220:223], v[124:127]
	v_mfma_f32_16x16x32_bf16 v[120:123], v[132:135], v[228:231], v[120:123]
	v_mfma_f32_16x16x32_bf16 v[116:119], v[160:163], v[228:231], v[116:119]
	v_mfma_f32_16x16x32_bf16 v[112:115], v[132:135], v[236:239], v[112:115]
	v_mfma_f32_16x16x32_bf16 v[108:111], v[160:163], v[236:239], v[108:111]
	v_mfma_f32_16x16x32_bf16 v[102:105], v[132:135], v[244:247], v[104:107]
	v_mfma_f32_16x16x32_bf16 v[98:101], v[160:163], v[244:247], v[98:101]
	v_mfma_f32_16x16x32_bf16 v[128:131], v[136:139], v[224:227], v[128:131]
	v_mfma_f32_16x16x32_bf16 v[124:127], v[164:167], v[224:227], v[124:127]
	v_mfma_f32_16x16x32_bf16 v[120:123], v[136:139], v[232:235], v[120:123]
	v_mfma_f32_16x16x32_bf16 v[116:119], v[164:167], v[232:235], v[116:119]
	v_mfma_f32_16x16x32_bf16 v[112:115], v[136:139], v[240:243], v[112:115]
	v_mfma_f32_16x16x32_bf16 v[108:111], v[164:167], v[240:243], v[108:111]
	v_mfma_f32_16x16x32_bf16 v[104:107], v[136:139], v[248:251], v[102:105]
	v_mfma_f32_16x16x32_bf16 v[100:103], v[164:167], v[248:251], v[98:101]
	s_setprio 0
	s_setprio 1
	v_mfma_f32_16x16x32_bf16 v[92:95], v[168:171], v[220:223], v[92:95]
	v_mfma_f32_16x16x32_bf16 v[88:91], v[204:207], v[220:223], v[88:91]
	v_mfma_f32_16x16x32_bf16 v[84:87], v[168:171], v[228:231], v[84:87]
	v_mfma_f32_16x16x32_bf16 v[80:83], v[204:207], v[228:231], v[80:83]
	v_mfma_f32_16x16x32_bf16 v[76:79], v[168:171], v[236:239], v[76:79]
	v_mfma_f32_16x16x32_bf16 v[72:75], v[204:207], v[236:239], v[72:75]
	v_mfma_f32_16x16x32_bf16 v[68:71], v[168:171], v[244:247], v[68:71]
	v_mfma_f32_16x16x32_bf16 v[64:67], v[204:207], v[244:247], v[64:67]
	v_mfma_f32_16x16x32_bf16 v[92:95], v[172:175], v[224:227], v[92:95]
	v_mfma_f32_16x16x32_bf16 v[88:91], v[216:219], v[224:227], v[88:91]
	v_mfma_f32_16x16x32_bf16 v[84:87], v[172:175], v[232:235], v[84:87]
	v_mfma_f32_16x16x32_bf16 v[80:83], v[216:219], v[232:235], v[80:83]
	v_mfma_f32_16x16x32_bf16 v[76:79], v[172:175], v[240:243], v[76:79]
	v_mfma_f32_16x16x32_bf16 v[72:75], v[216:219], v[240:243], v[72:75]
	v_mfma_f32_16x16x32_bf16 v[68:71], v[172:175], v[248:251], v[68:71]
	v_mfma_f32_16x16x32_bf16 v[64:67], v[216:219], v[248:251], v[64:67]
	s_setprio 0
	s_barrier
	s_add_i32 s20, s22, s91
	v_lshl_add_u64 v[98:99], v[176:177], 0, s[96:97]
	s_mov_b32 m0, s20
	ds_read_b128 v[220:223], v188 offset:49152
	ds_read_b128 v[224:227], v188 offset:50176
	ds_read_b128 v[228:231], v188 offset:51200
	ds_read_b128 v[232:235], v188 offset:52224
	ds_read_b128 v[236:239], v188 offset:53248
	ds_read_b128 v[240:243], v188 offset:54272
	ds_read_b128 v[244:247], v188 offset:55296
	ds_read_b128 v[248:251], v188 offset:56320
	global_load_lds_dwordx4 v[98:99], off
	v_lshl_add_u64 v[98:99], v[210:211], 0, s[96:97]
	s_add_i32 m0, s20, 0x2000
	s_add_i32 s20, s23, s91
	global_load_lds_dwordx4 v[98:99], off
	v_lshl_add_u64 v[98:99], v[212:213], 0, s[96:97]
	s_mov_b32 m0, s20
	s_nop 0
	global_load_lds_dwordx4 v[98:99], off
	v_lshl_add_u64 v[98:99], v[190:191], 0, s[96:97]
	s_add_i32 m0, s20, 0x2000
	s_nop 0
	global_load_lds_dwordx4 v[98:99], off
	v_lshl_add_u64 v[98:99], s[18:19], 0, v[140:141]
	s_mov_b32 m0, s5
	s_nop 0
	global_load_lds_dwordx4 v[98:99], off
	v_lshl_add_u64 v[98:99], s[18:19], 0, v[142:143]
	s_mov_b32 m0, s44
	s_nop 0
	global_load_lds_dwordx4 v[98:99], off
	s_waitcnt vmcnt(8)
	s_waitcnt lgkmcnt(0)
	s_barrier
	s_setprio 1
	v_mfma_f32_16x16x32_bf16 v[60:63], v[132:135], v[220:223], v[60:63]
	v_mfma_f32_16x16x32_bf16 v[56:59], v[160:163], v[220:223], v[56:59]
	v_mfma_f32_16x16x32_bf16 v[52:55], v[132:135], v[228:231], v[52:55]
	v_mfma_f32_16x16x32_bf16 v[48:51], v[160:163], v[228:231], v[48:51]
	v_mfma_f32_16x16x32_bf16 v[44:47], v[132:135], v[236:239], v[44:47]
	v_mfma_f32_16x16x32_bf16 v[40:43], v[160:163], v[236:239], v[40:43]
	v_mfma_f32_16x16x32_bf16 v[36:39], v[132:135], v[244:247], v[36:39]
	v_mfma_f32_16x16x32_bf16 v[32:35], v[160:163], v[244:247], v[32:35]
	v_mfma_f32_16x16x32_bf16 v[60:63], v[136:139], v[224:227], v[60:63]
	v_mfma_f32_16x16x32_bf16 v[56:59], v[164:167], v[224:227], v[56:59]
	v_mfma_f32_16x16x32_bf16 v[52:55], v[136:139], v[232:235], v[52:55]
	v_mfma_f32_16x16x32_bf16 v[48:51], v[164:167], v[232:235], v[48:51]
	v_mfma_f32_16x16x32_bf16 v[44:47], v[136:139], v[240:243], v[44:47]
	v_mfma_f32_16x16x32_bf16 v[40:43], v[164:167], v[240:243], v[40:43]
	v_mfma_f32_16x16x32_bf16 v[36:39], v[136:139], v[248:251], v[36:39]
	v_mfma_f32_16x16x32_bf16 v[32:35], v[164:167], v[248:251], v[32:35]
	s_setprio 0
	s_setprio 1
	v_mfma_f32_16x16x32_bf16 v[28:31], v[168:171], v[220:223], v[28:31]
	v_mfma_f32_16x16x32_bf16 v[24:27], v[204:207], v[220:223], v[24:27]
	v_mfma_f32_16x16x32_bf16 v[20:23], v[168:171], v[228:231], v[20:23]
	v_mfma_f32_16x16x32_bf16 v[16:19], v[204:207], v[228:231], v[16:19]
	v_mfma_f32_16x16x32_bf16 v[12:15], v[168:171], v[236:239], v[12:15]
	v_mfma_f32_16x16x32_bf16 v[8:11], v[204:207], v[236:239], v[8:11]
	v_mfma_f32_16x16x32_bf16 v[4:7], v[168:171], v[244:247], v[4:7]
	v_mfma_f32_16x16x32_bf16 v[0:3], v[204:207], v[244:247], v[0:3]
	v_mfma_f32_16x16x32_bf16 v[28:31], v[172:175], v[224:227], v[28:31]
	v_mfma_f32_16x16x32_bf16 v[24:27], v[216:219], v[224:227], v[24:27]
	v_mfma_f32_16x16x32_bf16 v[20:23], v[172:175], v[232:235], v[20:23]
	v_mfma_f32_16x16x32_bf16 v[16:19], v[216:219], v[232:235], v[16:19]
	v_mfma_f32_16x16x32_bf16 v[12:15], v[172:175], v[240:243], v[12:15]
	v_mfma_f32_16x16x32_bf16 v[8:11], v[216:219], v[240:243], v[8:11]
	v_mfma_f32_16x16x32_bf16 v[4:7], v[172:175], v[248:251], v[4:7]
	v_mfma_f32_16x16x32_bf16 v[0:3], v[216:219], v[248:251], v[0:3]
	s_setprio 0
	s_barrier
	s_add_u32 s27, s27, 0x100
	s_addc_u32 s28, s28, 0
	s_cmp_ge_i32 s16, s69
	s_mov_b64 s[18:19], s[16:17]
	s_cbranch_scc0 .LBB0_394
